# phase 2: wd/ad row pairs of both loop iterations requested at item start, ahead of the r|k|v staging loads
# speedup vs baseline: 1.0166x; 1.0011x over previous
; DI void rwkv_prep(const Params& p, int l, int item, char* smraw) {
;     ...
;   __syncthreads();
;   bf16_t* SR = A3 + 64 * 264;
;   {
;     const bool seqstart = (T0 & 2047) == 0;
;     uint4 sv[13];
; #pragma unroll
;     for (int i = 0; i < 13; ++i) {
;       const int idx = tid + 512 * i, row = idx / 96, c = idx - row * 96;
;       sv[i] = make_uint4(0, 0, 0, 0);
;       if (idx < 65 * 96 && (row > 0 || !seqstart)) sv[i] = *(const uint4*)(hb + (size_t)(T0 - 1 + row) * HS + C_R + c * 8);
;     }
; #pragma unroll
;     for (int i = 0; i < 13; ++i) {
;       const int idx = tid + 512 * i, row = idx / 96, c = idx - row * 96;
;       if (idx < 65 * 96) *(uint4*)(SR + row * 776 + c * 8) = sv[i];
;     }
;   }
; #pragma unroll
;   for (int idx = tid; idx < 64 * 16; idx += 512) {
;     const int tok = idx >> 4, c8 = idx & 15;
;     const size_t m = (size_t)(T0 + tok);
;     const uint4 z = *(const uint4*)(hb + m * HS + C_WD + c8 * 8);
;     uint4 zp = make_uint4(0, 0, 0, 0);
;     if (((T0 + tok) & 2047) != 0) zp = *(const uint4*)(hb + (m - 1) * HS + C_WD + c8 * 8);
.LBB0_322:
	s_mov_b64 s[4:5], s[10:11]
	s_load_dwordx2 s[6:7], s[4:5], 0xf0
	s_mov_b64 s[4:5], s[10:11]
	v_mov_b32_e32 v54, v201
	v_mov_b32_e32 v2, 0
	s_waitcnt lgkmcnt(0)
	s_add_u32 s40, s6, 0x32a4500
	s_addc_u32 s41, s7, 0
	s_lshl_b32 s10, s22, 6
	s_and_b32 s0, s22, 31
	s_cmp_eq_u32 s0, 0
	s_movk_i32 s0, 0x1860
	v_cmp_gt_i32_e32 vcc, s0, v54
	s_movk_i32 s0, 0x60
	s_cselect_b64 s[6:7], -1, 0
	v_cmp_gt_i32_e64 s[36:37], s0, v54
	s_and_b64 s[20:21], s[6:7], s[36:37]
	s_mov_b32 s0, 0x2aaaaaab
	s_xor_b64 s[20:21], s[20:21], -1
	v_mul_hi_i32 v3, v54, s0
	s_add_i32 s23, s10, -1
	s_and_b64 s[38:39], vcc, s[20:21]
	v_lshrrev_b32_e32 v0, 31, v3
	v_ashrrev_i32_e32 v55, 4, v3
	v_mov_b32_e32 v6, 0
	v_mov_b32_e32 v7, 0
	v_mov_b32_e32 v8, 0
	v_mov_b32_e32 v9, 0
	s_barrier
	v_ashrrev_i32_e32 v144, 4, v201
	v_add_u32_e32 v144, s10, v144
	v_mov_b64_e32 v[146:147], s[40:41]
	v_mad_i64_i32 v[146:147], s[98:99], v144, s87, v[146:147]
	v_and_b32_e32 v148, 15, v201
	v_lshlrev_b32_e32 v148, 4, v148
	v_mov_b32_e32 v149, 0
	v_lshl_add_u64 v[146:147], v[146:147], 0, v[148:149]
	s_lshl_b32 s98, s87, 5
	s_mov_b32 s99, 0
	v_lshl_add_u64 v[154:155], v[146:147], 0, s[98:99]
	v_add_co_u32_e32 v150, vcc, 0x1000, v146
	s_nop 0
	v_addc_co_u32_e32 v151, vcc, 0, v147, vcc
	global_load_dwordx4 v[128:131], v[150:151], off offset:2560
	v_mov_b32_e32 v132, 0
	v_mov_b32_e32 v133, 0
	v_mov_b32_e32 v134, 0
	v_mov_b32_e32 v135, 0
	v_and_b32_e32 v152, 0x7ff, v144
	v_cmp_ne_u32_e32 vcc, 0, v152
	s_and_saveexec_b64 s[100:101], vcc
	global_load_dwordx4 v[132:135], v[146:147], off offset:-1024
	s_mov_b64 exec, s[100:101]
	v_add_co_u32_e32 v150, vcc, 0x1000, v154
	s_nop 0
	v_addc_co_u32_e32 v151, vcc, 0, v155, vcc
	global_load_dwordx4 v[136:139], v[150:151], off offset:2560
	v_mov_b32_e32 v140, 0
	v_mov_b32_e32 v141, 0
	v_mov_b32_e32 v142, 0
	v_mov_b32_e32 v143, 0
	v_add_u32_e32 v152, 32, v144
	v_and_b32_e32 v152, 0x7ff, v152
	v_cmp_ne_u32_e32 vcc, 0, v152
	s_and_saveexec_b64 s[100:101], vcc
	global_load_dwordx4 v[140:143], v[154:155], off offset:-1024
	s_mov_b64 exec, s[100:101]
	s_and_saveexec_b64 s[20:21], s[38:39]
	s_cbranch_execz .LBB0_324
	v_add_u32_e32 v3, v55, v0
	s_movk_i32 s0, 0xffa0
	v_mul_lo_u32 v6, v3, s0
	v_add_u32_e32 v3, s23, v3
	v_mov_b64_e32 v[4:5], s[40:41]
	v_add_lshl_u32 v6, v6, v54, 3
	v_mad_i64_i32 v[4:5], s[38:39], v3, s87, v[4:5]
	v_ashrrev_i32_e32 v7, 31, v6
	v_lshl_add_u64 v[4:5], v[6:7], 1, v[4:5]
	v_add_co_u32_e32 v4, vcc, 0x1000, v4
	s_nop 1
	v_addc_co_u32_e32 v5, vcc, 0, v5, vcc
	global_load_dwordx4 v[6:9], v[4:5], off offset:1024

; DI void rwkv_prep(const Params& p, int l, int item, char* smraw) {
;     ...
; #pragma unroll
;   for (int idx = tid; idx < 64 * 16; idx += 512) {
;     const int tok = idx >> 4, c8 = idx & 15;
;     const size_t m = (size_t)(T0 + tok);
;     const uint4 z = *(const uint4*)(hb + m * HS + C_WD + c8 * 8);
;     uint4 zp = make_uint4(0, 0, 0, 0);
;     if (((T0 + tok) & 2047) != 0) zp = *(const uint4*)(hb + (m - 1) * HS + C_WD + c8 * 8);
;     const unsigned zz[4] = {z.x, z.y, z.z, z.w}, pp[4] = {zp.x, zp.y, zp.z, zp.w};
;     unsigned oo[4];
; #pragma unroll
;     for (int e = 0; e < 4; ++e) {
;       const float m0 = mu[768 + c8 * 8 + 2 * e], m1 = mu[768 + c8 * 8 + 2 * e + 1];
.LBB0_374:
	s_or_b64 exec, exec, s[6:7]
	s_waitcnt lgkmcnt(0)
	s_add_u32 s38, s4, s2
	s_movk_i32 s0, 0x400
	s_addc_u32 s39, s5, s3
	v_cmp_gt_i32_e32 vcc, s0, v54
	s_and_saveexec_b64 s[4:5], vcc
	s_cbranch_execz .LBB0_387
	v_and_b32_e32 v0, 15, v54
	s_waitcnt vmcnt(0)
	v_lshlrev_b32_e32 v6, 5, v0
	global_load_dwordx4 v[2:5], v6, s[38:39] offset:3088
	s_nop 0
	global_load_dwordx4 v[6:9], v6, s[38:39] offset:3072
	v_lshlrev_b32_e32 v18, 3, v0
	v_cmp_gt_u32_e64 s[36:37], 8, v0
	v_lshl_add_u32 v20, v0, 4, 0
	s_mov_b64 s[42:43], 0
	s_mov_b32 s96, 0
	v_mov_b32_e32 v19, v54
	s_branch .LBB0_377

; DI float bflo(unsigned u) { return __uint_as_float(u << 16); }
; DI float bfhi(unsigned u) { return __uint_as_float(u & 0xffff0000u); }
; DI void rwkv_prep(const Params& p, int l, int item, char* smraw) {
;     ...
;   for (int idx = tid; idx < 64 * 16; idx += 512) {
;     const int tok = idx >> 4, c8 = idx & 15;
;     const size_t m = (size_t)(T0 + tok);
;     const uint4 z = *(const uint4*)(hb + m * HS + C_WD + c8 * 8);
;     uint4 zp = make_uint4(0, 0, 0, 0);
;     if (((T0 + tok) & 2047) != 0) zp = *(const uint4*)(hb + (m - 1) * HS + C_WD + c8 * 8);
;     const unsigned zz[4] = {z.x, z.y, z.z, z.w}, pp[4] = {zp.x, zp.y, zp.z, zp.w};
;     unsigned oo[4];
; #pragma unroll
;     for (int e = 0; e < 4; ++e) {
;       const float m0 = mu[768 + c8 * 8 + 2 * e], m1 = mu[768 + c8 * 8 + 2 * e + 1];
;       float x0 = bflo(zz[e]), x1 = bfhi(zz[e]);
;       x0 = x0 + (bflo(pp[e]) - x0) * m0; x1 = x1 + (bfhi(pp[e]) - x1) * m1;
;       if (c8 < 8) { x0 = 1.f - 2.f * __builtin_amdgcn_rcpf(__expf(2.f * x0) + 1.f); x1 = 1.f - 2.f * __builtin_amdgcn_rcpf(__expf(2.f * x1) + 1.f); }
.LBB0_377:
	v_ashrrev_i32_e32 v21, 4, v19
	v_add_u32_e32 v14, s10, v21
	v_mov_b64_e32 v[10:11], s[40:41]
	v_mad_i64_i32 v[10:11], s[6:7], v14, s87, v[10:11]
	v_lshlrev_b32_e32 v0, 1, v18
	v_lshl_add_u64 v[22:23], v[10:11], 0, v[0:1]
	v_add_co_u32_e32 v10, vcc, 0x1000, v22
	v_and_b32_e32 v0, 0x7ff, v14
	s_nop 0
	v_addc_co_u32_e32 v11, vcc, 0, v23, vcc
	s_waitcnt vmcnt(0)
	s_cmp_eq_u32 s96, 0
	s_cbranch_scc0 .Lwd_it1
	v_mov_b32_e32 v10, v128
	v_mov_b32_e32 v11, v129
	v_mov_b32_e32 v12, v130
	v_mov_b32_e32 v13, v131
	v_mov_b32_e32 v14, v132
	v_mov_b32_e32 v15, v133
	v_mov_b32_e32 v16, v134
	v_mov_b32_e32 v17, v135
	s_branch .Lwd_join
.Lwd_it1:
	v_mov_b32_e32 v10, v136
	v_mov_b32_e32 v11, v137
	v_mov_b32_e32 v12, v138
	v_mov_b32_e32 v13, v139
	v_mov_b32_e32 v14, v140
	v_mov_b32_e32 v15, v141
	v_mov_b32_e32 v16, v142
	v_mov_b32_e32 v17, v143
.Lwd_join:
	s_add_i32 s96, s96, 1
	v_lshlrev_b32_e32 v22, 16, v10
	v_and_b32_e32 v23, 0xffff0000, v10
	v_lshlrev_b32_e32 v24, 16, v14
	v_and_b32_e32 v25, 0xffff0000, v14
	v_pk_add_f32 v[24:25], v[24:25], v[22:23] neg_lo:[0,1] neg_hi:[0,1]
	s_nop 0
	v_pk_fma_f32 v[22:23], v[6:7], v[24:25], v[22:23]
	s_and_saveexec_b64 s[6:7], s[36:37]
	s_cbranch_execz .LBB0_381
	v_add_f32_e32 v0, v22, v22
	v_mul_f32_e32 v0, 0x3fb8aa3b, v0
	v_add_f32_e32 v10, v23, v23
	v_exp_f32_e32 v0, v0
	v_mul_f32_e32 v10, 0x3fb8aa3b, v10
	v_exp_f32_e32 v10, v10
	v_add_f32_e32 v0, 1.0, v0
	v_rcp_f32_e32 v22, v0
	v_add_f32_e32 v0, 1.0, v10
	v_rcp_f32_e32 v23, v0
	s_nop 0
	v_pk_fma_f32 v[22:23], v[22:23], -2.0, 1.0 op_sel_hi:[1,0,0]
